# P1 tile group 3 swapped between workgroup pairs (forward walkers take CG, reversed walkers CH): larger natural phase offset between the two halves of an XCC
# speedup vs baseline: 1.0071x; 1.0026x over previous
; #define LAS __attribute__((address_space(3)))
; __device__ __forceinline__ int otid(int wave) { return wave * 64 + olane(); }
; __global__ void __launch_bounds__(512, 2) mk_fwd(Args args) {
;     ...
;                 LAS float* lb = (LAS float*)(F.lds + 131072); P.lbias = lb; const int t_ = otid(F.wave);
; #pragma unroll
;                 for (int i = 0; i < 4; ++i) { const int e = i * 512 + t_, slot = e >> 8; const int pn_ = (P1_MAP == 1) ? (((cid >> 3) & 7) + 8 * (slot & 3)) : (4 * slot + (cid >> 6)); lb[e] = P.biasp[256 * pn_ + (e & 255)]; }
;                 if (splitb && (SPLIT_BAR & 2) && L > 0) xcdl_wait_t0(bar);
;                 if (psync && (PSYNC & 2) && L > 0) psync_wait((unsigned*)(ctl + CW_PSYNC + (2 * (L - 1) + 1) * 1024 + 16 * (8 * (cid & 7) + ((cid >> 3) & 7))), (unsigned*)(ctl + CW_TMO), 0x910u);
;                 __syncthreads(); }
.LBB0_174:
	s_lshl_b32 s34, s58, 2
	s_or_b32 s2, s34, 1
	s_cmp_le_i32 s66, s2
	s_cselect_b64 s[0:1], -1, 0
	s_cmp_lt_i32 s2, s67
	s_cselect_b64 s[2:3], -1, 0
	v_writelane_b32 v254, s60, 52
	s_and_b64 s[2:3], s[0:1], s[2:3]
	s_andn2_b64 vcc, exec, s[2:3]
	v_writelane_b32 v254, s61, 53
	v_writelane_b32 v254, s34, 54
	s_cbranch_vccnz .LBB0_398
	v_readlane_b32 s0, v254, 11
	s_mov_b64 s[42:43], s[82:83]
	v_readlane_b32 s1, v254, 12
	s_lshl_b32 s78, s58, 13
	v_mbcnt_lo_u32_b32 v0, -1, 0
	v_mbcnt_hi_u32_b32 v0, -1, v0
	s_and_b64 s[0:1], s[88:89], s[0:1]
	v_add_u32_e32 v2, s70, v0
	s_lshl_b64 s[6:7], s[78:79], 2
	v_lshrrev_b32_e32 v0, 6, v2
	s_add_u32 s6, s42, s6
	v_and_b32_e32 v0, 0xfffffc, v0
	v_readlane_b32 s8, v253, 7
	s_addc_u32 s7, s43, s7
	v_and_b32_e32 v3, 0xff, v2
	v_add_u32_e32 v0, s8, v0
	v_and_b32_e32 v1, -4, v0
	v_cmp_eq_u32_e64 s[98:99], 12, v1
	v_cndmask_b32_e64 v1, 0, 2, s[98:99]
	v_xor_b32_e32 v0, v0, v1
	s_add_u32 s6, s6, 0x1d80000
	v_lshl_or_b32 v0, v0, 8, v3
	s_addc_u32 s7, s7, 0
	v_ashrrev_i32_e32 v1, 31, v0
	v_lshl_add_u64 v[0:1], v[0:1], 2, s[6:7]
	flat_load_dword v4, v[0:1]
	v_lshl_add_u32 v0, v2, 2, 0
	v_add_u32_e32 v1, 0x200, v2
	v_add_u32_e32 v5, 0x20000, v0
	v_lshrrev_b32_e32 v0, 6, v1
	v_and_b32_e32 v0, 0xfffffc, v0
	v_add_u32_e32 v0, s8, v0
	v_and_b32_e32 v1, -4, v0
	v_cmp_eq_u32_e64 s[98:99], 12, v1
	v_cndmask_b32_e64 v1, 0, 2, s[98:99]
	v_xor_b32_e32 v0, v0, v1
	v_lshl_or_b32 v0, v0, 8, v3
	v_ashrrev_i32_e32 v1, 31, v0
	v_lshl_add_u64 v[0:1], v[0:1], 2, s[6:7]
	s_andn2_b64 vcc, exec, s[0:1]
	flat_load_dword v6, v[0:1]
	v_add_u32_e32 v0, 0x400, v2
	v_lshrrev_b32_e32 v0, 6, v0
	v_and_b32_e32 v0, 0xfffffc, v0
	v_add_u32_e32 v0, s8, v0
	v_and_b32_e32 v1, -4, v0
	v_cmp_eq_u32_e64 s[98:99], 12, v1
	v_cndmask_b32_e64 v1, 0, 2, s[98:99]
	v_xor_b32_e32 v0, v0, v1
	v_lshl_or_b32 v0, v0, 8, v3
	v_ashrrev_i32_e32 v1, 31, v0
	v_lshl_add_u64 v[0:1], v[0:1], 2, s[6:7]
	flat_load_dword v7, v[0:1]
	v_add_u32_e32 v0, 0x600, v2
	v_lshrrev_b32_e32 v0, 6, v0
	v_and_b32_e32 v0, 0xfffffc, v0
	v_add_u32_e32 v0, s8, v0
	v_and_b32_e32 v1, -4, v0
	v_cmp_eq_u32_e64 s[98:99], 12, v1
	v_cndmask_b32_e64 v1, 0, 2, s[98:99]
	v_xor_b32_e32 v0, v0, v1
	v_lshl_or_b32 v0, v0, 8, v3
	v_ashrrev_i32_e32 v1, 31, v0
	v_lshl_add_u64 v[0:1], v[0:1], 2, s[6:7]
	flat_load_dword v8, v[0:1]
	s_nop 0
	s_nop 0
	s_nop 0
	s_waitcnt vmcnt(0) lgkmcnt(0)
	ds_write_b32 v5, v4
	ds_write_b32 v5, v6 offset:2048
	ds_write_b32 v5, v7 offset:4096
	ds_write_b32 v5, v8 offset:6144
	s_cbranch_vccnz .LBB0_190
	v_mbcnt_lo_u32_b32 v0, -1, 0
	v_mbcnt_hi_u32_b32 v0, -1, v0
	s_nop 0
	v_cmp_eq_u32_e32 vcc, 0, v0
	s_and_saveexec_b64 s[6:7], vcc
	s_cbranch_execz .LBB0_189
	s_lshl_b32 s16, s23, 1
	s_add_u32 s0, s26, 0x6000
	s_addc_u32 s1, s27, 0
	s_add_u32 s0, s0, s16
	s_addc_u32 s1, s1, 0
	v_mov_b32_e32 v0, s21
	ds_read_b32 v0, v0
	s_waitcnt vmcnt(0) lgkmcnt(0)
	v_readfirstlane_b32 s8, v0
	s_mov_b64 s[10:11], exec
	s_mov_b32 exec_lo, -1
	s_mov_b32 exec_hi, 0
	v_mbcnt_lo_u32_b32 v2, -1, 0
	v_lshlrev_b32_e32 v2, 2, v2
	v_mov_b32_e32 v1, s8
	s_mov_b32 s9, 0

;     __device__ __forceinline__ bool next(int i, GUnit& u) const {
;         const int L = i * G + c; if (L >= 64 * 32) return false;
;         const int xcd = L & 7, off = L >> 3;
;     ...
;         const int j = off & 31, i_ = off >> 5, a = j >> 3, b = j & 7;
;         const int pm = 8 * xcd + 4 * (i_ >> 2) + a, pn = b + 8 * (i_ & 3);
;     ...
;         const int pm = 8 * xcd + (off & 7); int pn = off >> 3;
;         if (P1_REV && G == 256 && (pn & 2)) pn = 4 * (7 - (pn >> 2)) + (pn & 3);
;     ...
;         u.pm = pm; u.pn = pn; u.nt = 16;
;         int kind, t;
;         if (pn < 4) { kind = K_UA; t = pn; } else if (pn < 6) { kind = K_V; t = pn - 4; } else if (pn < 8) { kind = K_BZ; t = pn - 6; } else if (pn < 10) { kind = K_BG; t = pn - 8; }
;         else if (pn < 14) { kind = K_CH; t = pn - 10; } else if (pn < 16) { kind = K_CG; t = pn - 14; } else if (pn < 28) { kind = K_MG; t = pn - 16; } else { kind = K_PG; t = pn - 28; }
;         u.kind = kind; u.t = t;
;         const char* xa = XB + (size_t)pm * 256 * 1024 * 2; const char* wb = WT + (size_t)pn * 256 * 1024 * 2;
;         const bool sw = (kind == K_V) || (kind == K_BZ);
;         u.a = sw ? wb : xa; u.b = sw ? xa : wb;
;         return true;
;     }
;     __device__ __forceinline__ int first_wmode(const GUnit& u, int ui) const {
;         static_assert(P1_MAP == 0, "first_wmode assumes pn advances by 4 per unit");
;         if (ui == 0) return 0;
;         const int pp = (P1_REV && G == 256 && (u.pn & 2)) ? u.pn + 4 : u.pn - 4; const bool s16 = (pp >= 4 && pp < 10) || (pp >= 14 && pp < 16);
;         return s16 ? 2 : 1;
;     }
.LBB0_195:
	s_add_i32 s92, s1, 1
	s_mul_i32 s93, s92, s96
	s_add_i32 s93, s93, s52
	s_cmpk_lt_i32 s93, 0x800
	s_cselect_b64 s[76:77], -1, 0
	s_cmpk_gt_i32 s93, 0x7ff
	s_cbranch_scc1 .LBB0_197
	s_lshl_b32 s0, s93, 3
	s_and_b32 s0, s0, 56
	s_bfe_u32 s7, s93, 0x30003
	s_or_b32 s0, s0, s7
	s_ashr_i32 s7, s93, 6
	s_and_b32 s8, s7, -4
	s_and_b32 s9, s7, 3
	s_sub_i32 s8, s9, s8
	s_add_i32 s10, s8, 28
	v_readlane_b32 s8, v253, 5
	v_readlane_b32 s9, v253, 6
	s_and_b64 s[8:9], s[8:9], exec
	s_cselect_b32 s8, s7, s10
	s_lshr_b32 s10, s8, 2
	s_cmp_eq_u32 s10, 3
	s_cselect_b32 s10, 2, 0
	s_xor_b32 s8, s8, s10
	s_and_b32 s7, s8, -4
	s_lshl_b32 s0, s0, 19
	s_add_u32 s0, s36, s0
	s_addc_u32 s10, s37, 0
	s_ashr_i32 s9, s8, 31
	s_lshl_b64 s[8:9], s[8:9], 19
	s_add_u32 s8, s56, s8
	s_addc_u32 s9, s57, s9
	s_cmp_eq_u32 s7, 4
	s_cselect_b32 s29, s9, s10
	s_cselect_b32 s28, s8, s0
	s_cselect_b32 s31, s10, s9
	s_cselect_b32 s30, s0, s8
.LBB0_197:
	s_mov_b32 s0, 0
	s_cmp_eq_u32 s1, 0
	s_mov_b32 s16, 0
	s_cbranch_scc1 .LBB0_199
	s_lshr_b32 s7, s40, 2
	s_cmp_eq_u32 s7, 3
	s_cselect_b32 s7, 2, 0
	s_xor_b32 s7, s40, s7
	s_bitcmp0_b32 s7, 1
	s_cselect_b64 s[8:9], -1, 0
	s_or_b64 s[8:9], s[54:55], s[8:9]
	s_and_b64 s[8:9], s[8:9], exec
	s_cselect_b32 s1, -4, 4
	s_add_i32 s1, s1, s7
	s_lshr_b32 s7, s1, 2
	s_cmp_eq_u32 s7, 3
	s_cselect_b32 s7, 2, 0
	s_xor_b32 s1, s1, s7
	s_add_i32 s7, s1, -4
	s_cmp_lt_u32 s7, 6
	s_cselect_b64 s[8:9], -1, 0
	s_and_b32 s1, s1, -2
	s_cmp_eq_u32 s1, 14
	s_cselect_b64 s[10:11], -1, 0
	s_or_b64 s[8:9], s[8:9], s[10:11]
	s_and_b64 s[8:9], s[8:9], exec
	s_cselect_b32 s16, 2, 1

;     __device__ __forceinline__ bool next(int i, GUnit& u) const {
;     ...
;         const int pm = 8 * xcd + (off & 7); int pn = off >> 3;
;         if (P1_REV && G == 256 && (pn & 2)) pn = 4 * (7 - (pn >> 2)) + (pn & 3);
;     ...
;         u.pm = pm; u.pn = pn; u.nt = 16;
;         int kind, t;
;         if (pn < 4) { kind = K_UA; t = pn; } else if (pn < 6) { kind = K_V; t = pn - 4; } else if (pn < 8) { kind = K_BZ; t = pn - 6; } else if (pn < 10) { kind = K_BG; t = pn - 8; }
;         else if (pn < 14) { kind = K_CH; t = pn - 10; } else if (pn < 16) { kind = K_CG; t = pn - 14; } else if (pn < 28) { kind = K_MG; t = pn - 16; } else { kind = K_PG; t = pn - 28; }
;         u.kind = kind; u.t = t;
.LBB0_367:
	s_andn2_b64 vcc, exec, s[76:77]
	s_mov_b64 s[0:1], -1
	global_store_dwordx4 v[144:145], v[148:151], off
	s_cbranch_vccnz .LBB0_194
	s_ashr_i32 s6, s93, 6
	s_and_b32 s0, s6, -4
	s_and_b32 s1, s6, 3
	s_sub_i32 s0, s1, s0
	s_add_i32 s7, s0, 28
	v_readlane_b32 s0, v253, 5
	v_readlane_b32 s1, v253, 6
	s_and_b64 s[0:1], s[0:1], exec
	s_cselect_b32 s40, s6, s7
	s_lshr_b32 s7, s40, 2
	s_cmp_eq_u32 s7, 3
	s_cselect_b32 s7, 2, 0
	s_xor_b32 s40, s40, s7
	s_mov_b32 s41, 0
	s_cmp_lt_i32 s40, 4
	s_mov_b32 s6, s40
	s_cbranch_scc1 .LBB0_393
	s_cmp_gt_u32 s40, 5
	s_mov_b64 s[0:1], -1
	s_cbranch_scc0 .LBB0_391
	s_cmp_gt_u32 s40, 7
	s_cbranch_scc0 .LBB0_388
	s_cmp_gt_u32 s40, 9
	s_cbranch_scc0 .LBB0_385
	s_cmp_gt_u32 s40, 13
	s_cbranch_scc0 .LBB0_382
	s_cmp_gt_u32 s40, 15
	s_cbranch_scc0 .LBB0_379
	s_cmp_gt_u32 s40, 27
	s_cbranch_scc0 .LBB0_376
	s_sub_i32 s6, s40, 28
	s_mov_b64 s[0:1], 0
